# baseline (speedup 1.0000x reference)
; DI bf16x8 pack8(const float* a) { u32x4 w = {cvtpk(a[0], a[1]), cvtpk(a[2], a[3]), cvtpk(a[4], a[5]), cvtpk(a[6], a[7])}; return *reinterpret_cast<bf16x8*>(&w); }
; DI int tid_() { int t = threadIdx.x; asm volatile("" : "+v"(t)); return t; }
; DI int bid_() { int b = blockIdx.x; asm volatile("" : "+s"(b)); return b; }
; DI void phase_norm(const float* x, const float* g, u16* out) {
;   const int wid = tid_() >> 6, lane = tid_() & 63;
;   for (int row = bid_() * 8 + wid; row < TG; row += gridDim.x * 8) {
;     const float* xr = x + (size_t)row * 1024;
;     float4 v[4]; float ss = 0.f;
; #pragma unroll
;     for (int i = 0; i < 2; ++i) for (int h = 0; h < 2; ++h) { float4 t = *reinterpret_cast<const float4*>(xr + i * 512 + lane * 8 + h * 4); v[2 * i + h] = t;
;       ss += t.x * t.x + t.y * t.y + t.z * t.z + t.w * t.w; }
;     ss = wave_sum_l(ss, lane);
;     const float r = rsqrtf(ss * (1.f / 1024.f) + EPS);
; #pragma unroll
;     for (int i = 0; i < 2; ++i) { const float4 g0 = *reinterpret_cast<const float4*>(g + i * 512 + lane * 8), g1 = *reinterpret_cast<const float4*>(g + i * 512 + lane * 8 + 4);
;       float a[8] = {v[2 * i].x * r * g0.x, v[2 * i].y * r * g0.y, v[2 * i].z * r * g0.z, v[2 * i].w * r * g0.w,
;                     v[2 * i + 1].x * r * g1.x, v[2 * i + 1].y * r * g1.y, v[2 * i + 1].z * r * g1.z, v[2 * i + 1].w * r * g1.w};
;       *reinterpret_cast<bf16x8*>(out + (size_t)row * 1024 + i * 512 + lane * 8) = pack8(a); }
;   }
; }
.LBB0_43:
	s_and_b64 vcc, exec, s[6:7]
	s_cbranch_vccz .LBB0_48
	s_waitcnt vmcnt(0)
	v_mov_b32_e32 v0, v232
	s_mov_b32 s2, s98
	v_ashrrev_i32_e32 v1, 6, v0
	v_mov_b32_e32 v0, v232
	s_nop 0
	v_lshl_add_u32 v20, s2, 3, v1
	v_cmp_gt_i32_e32 vcc, s77, v20
	s_and_saveexec_b64 s[38:39], vcc
	s_cbranch_execz .LBB0_47
	s_lshl_b32 s2, s79, 12
	s_add_u32 s6, s72, s2
	v_and_b32_e32 v0, 63, v0
	s_addc_u32 s7, s73, 0
	v_lshlrev_b32_e32 v96, 5, v0
	v_lshl_add_u64 v[24:25], s[6:7], 0, v[96:97]
	v_readlane_b32 s6, v255, 17
	v_lshl_add_u64 v[22:23], s[74:75], 0, v[96:97]
	v_lshlrev_b32_e32 v1, 2, v0
	v_lshlrev_b32_e32 v96, 4, v0
	v_readlane_b32 s7, v255, 18
	v_xor_b32_e32 v30, 64, v1
	v_xor_b32_e32 v31, 0x80, v1
	v_lshl_add_u64 v[26:27], s[6:7], 0, v[96:97]
	global_load_dwordx4 v[40:43], v[24:25], off offset:16
	global_load_dwordx4 v[44:47], v[24:25], off
	global_load_dwordx4 v[48:51], v[24:25], off offset:2064
	global_load_dwordx4 v[52:55], v[24:25], off offset:2048
	s_mov_b64 s[40:41], 0
.LBB0_46:
	v_ashrrev_i32_e32 v21, 31, v20
	v_lshlrev_b64 v[0:1], 12, v[20:21]
	v_lshl_add_u64 v[12:13], v[22:23], 0, v[0:1]
	global_load_dwordx4 v[4:7], v[12:13], off offset:16
	global_load_dwordx4 v[8:11], v[12:13], off
	global_load_dwordx4 v[56:59], v[12:13], off offset:2064
	global_load_dwordx4 v[60:63], v[12:13], off offset:2048
	s_waitcnt vmcnt(3)
	v_pk_mul_f32 v[16:17], v[4:5], v[4:5]
	s_waitcnt vmcnt(2)
	v_pk_mul_f32 v[14:15], v[8:9], v[8:9]
	v_pk_mul_f32 v[0:1], v[10:11], v[10:11]
	v_pk_mul_f32 v[2:3], v[6:7], v[6:7]
	v_mov_b32_e32 v18, v14
	v_mov_b32_e32 v19, v16
	v_mov_b32_e32 v16, v15
	v_pk_add_f32 v[14:15], v[18:19], v[16:17]
	v_mov_b32_e32 v16, v0
	v_mov_b32_e32 v17, v2
	v_pk_add_f32 v[14:15], v[14:15], v[16:17]
	v_mov_b32_e32 v2, v1
	v_pk_add_f32 v[16:17], v[14:15], v[2:3]
	v_add_f32_e32 v16, v16, v17
	s_waitcnt vmcnt(1)
	v_pk_mul_f32 v[34:35], v[56:57], v[56:57]
	s_waitcnt vmcnt(0)
	v_pk_mul_f32 v[32:33], v[60:61], v[60:61]
	v_pk_mul_f32 v[18:19], v[62:63], v[62:63]
	v_pk_mul_f32 v[28:29], v[58:59], v[58:59]
	v_mov_b32_e32 v36, v32
	v_mov_b32_e32 v37, v34
	v_mov_b32_e32 v34, v33
	v_pk_add_f32 v[32:33], v[36:37], v[34:35]
	v_mov_b32_e32 v34, v18
	v_mov_b32_e32 v35, v28
	v_pk_add_f32 v[32:33], v[32:33], v[34:35]
	v_mov_b32_e32 v28, v19
	v_pk_add_f32 v[18:19], v[32:33], v[28:29]
	s_nop 0
	v_add_f32_e32 v16, v16, v18
	v_add_f32_e32 v16, v16, v19
	s_nop 1
	v_add_f32_dpp v16, v16, v16 quad_perm:[1,0,3,2] row_mask:0xf bank_mask:0xf bound_ctrl:1
	s_nop 1
	v_add_f32_dpp v16, v16, v16 quad_perm:[2,3,0,1] row_mask:0xf bank_mask:0xf bound_ctrl:1
	s_nop 1
	v_add_f32_dpp v16, v16, v16 row_half_mirror row_mask:0xf bank_mask:0xf bound_ctrl:1
	s_nop 1
	v_add_f32_dpp v16, v16, v16 row_mirror row_mask:0xf bank_mask:0xf bound_ctrl:1
	ds_bpermute_b32 v17, v30, v16
	s_waitcnt lgkmcnt(0)
	v_add_f32_e32 v16, v16, v17
	ds_bpermute_b32 v17, v31, v16
	s_waitcnt lgkmcnt(0)
	v_add_f32_e32 v16, v16, v17
	v_fmamk_f32 v16, v16, 0x3a800000, v233
	v_cmp_gt_f32_e32 vcc, s94, v16
	v_mul_f32_e32 v17, 0x4b800000, v16
	s_nop 0
	v_cndmask_b32_e32 v16, v16, v17, vcc
	v_rsq_f32_e32 v16, v16
	s_nop 0
	v_mul_f32_e32 v17, 0x45800000, v16
	v_cndmask_b32_e32 v36, v16, v17, vcc
	v_lshlrev_b64 v[16:17], 11, v[20:21]
	v_lshl_add_u64 v[28:29], v[26:27], 0, v[16:17]
	v_mul_f32_e32 v4, v4, v36
	v_mul_f32_e32 v8, v8, v36
	v_mul_f32_e32 v9, v9, v36
	v_mul_f32_e32 v10, v10, v36
	v_mul_f32_e32 v11, v11, v36
	v_mul_f32_e32 v0, v56, v36
	v_mul_f32_e32 v12, v60, v36
	v_add_u32_e32 v20, s99, v20
	v_cmp_lt_i32_e32 vcc, s78, v20
	s_or_b64 s[40:41], vcc, s[40:41]
	v_mul_f32_e32 v16, v40, v4
	v_mul_f32_e32 v4, v5, v36
	v_mul_f32_e32 v17, v41, v4
	v_mul_f32_e32 v4, v6, v36
	v_mul_f32_e32 v18, v42, v4
	v_mul_f32_e32 v4, v7, v36
	v_mul_f32_e32 v7, v43, v4
	v_mul_f32_e32 v8, v44, v8
	v_mul_f32_e32 v9, v45, v9
	v_mul_f32_e32 v10, v46, v10
	v_mul_f32_e32 v11, v47, v11
	v_cvt_pk_bf16_f32 v4, v8, v9
	v_cvt_pk_bf16_f32 v5, v10, v11
	v_cvt_pk_bf16_f32 v6, v16, v17
	v_cvt_pk_bf16_f32 v7, v18, v7
	global_store_dwordx4 v[28:29], v[4:7], off
	s_nop 1
	v_mul_f32_e32 v4, v0, v48
	v_mul_f32_e32 v0, v57, v36
	v_mul_f32_e32 v8, v12, v52
	v_mul_f32_e32 v12, v61, v36
	v_mul_f32_e32 v5, v0, v49
	v_mul_f32_e32 v0, v58, v36
	v_mul_f32_e32 v9, v12, v53
	v_mul_f32_e32 v12, v62, v36
	v_mul_f32_e32 v6, v0, v50
	v_mul_f32_e32 v0, v59, v36
	v_mul_f32_e32 v10, v12, v54
	v_mul_f32_e32 v12, v63, v36
	v_mul_f32_e32 v3, v0, v51
	v_mul_f32_e32 v11, v12, v55
	v_cvt_pk_bf16_f32 v0, v8, v9
	v_cvt_pk_bf16_f32 v1, v10, v11
	v_cvt_pk_bf16_f32 v2, v4, v5
	v_cvt_pk_bf16_f32 v3, v6, v3
	global_store_dwordx4 v[28:29], v[0:3], off offset:1024
	s_andn2_b64 exec, exec, s[40:41]
	s_cbranch_execnz .LBB0_46
